# FoX loop: one static s_setprio 1 for the younger wave half (waves 4-7) before the loop, reset after it; no per-segment flips
# speedup vs baseline: 1.0026x; 1.0026x over previous
.Lfx_pk1:
	s_waitcnt vmcnt(0) lgkmcnt(0)
	s_barrier
	s_cmp_lt_i32 s41, 0
	s_cbranch_scc1 .LBB0_560
	v_mov_b64_e32 v[16:17], 0
	v_mov_b64_e32 v[18:19], 0
	v_mov_b64_e32 v[20:21], 0
	v_mov_b64_e32 v[22:23], 0
	v_mov_b64_e32 v[24:25], 0
	v_mov_b64_e32 v[26:27], 0
	v_mov_b64_e32 v[28:29], 0
	v_mov_b64_e32 v[30:31], 0
	v_mov_b64_e32 v[32:33], 0
	v_mov_b64_e32 v[34:35], 0
	v_mov_b64_e32 v[36:37], 0
	v_mov_b64_e32 v[38:39], 0
	v_mov_b64_e32 v[40:41], 0
	v_mov_b64_e32 v[42:43], 0
	v_mov_b64_e32 v[44:45], 0
	v_mov_b64_e32 v[46:47], 0
	v_mov_b64_e32 v[48:49], 0
	v_mov_b64_e32 v[50:51], 0
	v_mov_b64_e32 v[52:53], 0
	v_mov_b64_e32 v[54:55], 0
	v_mov_b64_e32 v[56:57], 0
	v_mov_b64_e32 v[58:59], 0
	v_mov_b64_e32 v[60:61], 0
	v_mov_b64_e32 v[62:63], 0
	v_mov_b64_e32 v[64:65], 0
	v_mov_b64_e32 v[66:67], 0
	v_mov_b64_e32 v[68:69], 0
	v_mov_b64_e32 v[70:71], 0
	v_mov_b64_e32 v[72:73], 0
	v_mov_b64_e32 v[74:75], 0
	v_mov_b64_e32 v[76:77], 0
	v_mov_b64_e32 v[78:79], 0
	v_mov_b32_e32 v192, 0xe0ad78ec
	v_mov_b32_e32 v162, 0
	s_lshl_b32 s50, s42, 6
	s_lshl_b32 s51, s42, 14
	s_sub_i32 s62, s62, s50
	s_add_i32 s62, s62, 30
	s_mov_b32 s63, 0
	s_mov_b32 s76, 0
	s_mov_b32 s77, 0x10200
	s_mov_b64 s[80:81], 0
	s_cmp_eq_u32 s42, 0
	s_cbranch_scc1 .Lfx_body
	s_setprio 1
	s_barrier

.Lfx_nogp:
	s_setprio 0
	s_barrier
	s_cmp_lg_u32 s42, 0
	s_cbranch_scc1 .Lfx_aligned
	s_barrier
